# pass-1 GLA: V copies folded into their consumers + trivial wait ladder dropped (-31 instr/unit); pass-1 SSD: the 32 xv loads use scalar bases (11 v_add_co/v_addc_co pairs -> SALU)
# baseline (speedup 1.0000x reference)
; #define LAS __attribute__((address_space(3)))
; template <int PASS>
; __device__ __forceinline__ void gla_unit(LAS unsigned char* lds, int ch, int h, const bf16* PROJ, const bf16* GT, bf16* STG, float* DECG, bf16* OMIX, const float* gla_norm) {
;     ...
;         OFFS[(d * 4 + qt) * 64 + kk] = d ? c[0] : c[15];
;         { const int vcol = tid & 127, q4 = tid >> 7; const bf16* vp = PROJ + (m0 + 16 * q4) * LDP + PV + h * 128 + vcol; unsigned vv[16];
; #pragma unroll
;           for (int jj = 0; jj < 16; ++jj) vv[jj] = vp[(size_t)jj * LDP];
; #pragma unroll
;           for (int jj = 0; jj < 16; ++jj) asm volatile("" : "+v"(vv[jj]));
;           v4u w0, w1; w0.x = vv[0] | (vv[1] << 16); w0.y = vv[2] | (vv[3] << 16); w0.z = vv[4] | (vv[5] << 16); w0.w = vv[6] | (vv[7] << 16);
;           w1.x = vv[8] | (vv[9] << 16); w1.y = vv[10] | (vv[11] << 16); w1.z = vv[12] | (vv[13] << 16); w1.w = vv[14] | (vv[15] << 16);
;           *(LAS v4u*)(VT + vcol * RS + q4 * 32) = w0; *(LAS v4u*)(VT + vcol * RS + q4 * 32 + 16) = w1; }
;         __syncthreads();
;         float off = 0.f, tot = 0.f;
; #pragma unroll
;         for (int q2 = 0; q2 < 4; ++q2) { const float t = OFFS[(d * 4 + q2) * 64 + kk]; tot += t; if (d ? (q2 > qt) : (q2 < qt)) off += t; }
.LBB0_764:
	s_or_b64 exec, exec, s[0:1]
	v_ashrrev_i32_e32 v5, 7, v114
	v_and_b32_e32 v3, 0x7f, v114
	v_lshlrev_b32_e32 v115, 2, v113
	v_mul_u32_u24_e32 v3, 0x90, v3
	v_lshlrev_b32_e32 v5, 5, v5
	v_add3_u32 v3, 0, v3, v5
	s_mov_b64 s[0:1], 0
	v_lshlrev_b32_e32 v35, 10, v55
	v_lshlrev_b32_e32 v25, 8, v36
	v_add_u32_e32 v26, s70, v35
	v_cndmask_b32_e32 v24, v83, v18, vcc
	v_add3_u32 v25, v26, v25, v115
	ds_write_b32 v25, v24
	v_lshl_or_b32 v24, v161, 16, v160
	v_lshl_or_b32 v25, v163, 16, v162
	v_lshl_or_b32 v26, v165, 16, v164
	v_lshl_or_b32 v27, v167, 16, v166
	s_waitcnt vmcnt(0)
	v_lshl_or_b32 v28, v169, 16, v168
	v_lshl_or_b32 v29, v171, 16, v170
	v_lshl_or_b32 v30, v173, 16, v172
	v_lshl_or_b32 v31, v175, 16, v174
	ds_write_b128 v3, v[24:27] offset:55296
	ds_write_b128 v3, v[28:31] offset:55312
	v_add_u32_e32 v3, s70, v115
	v_add_u32_e32 v3, v3, v35
	s_waitcnt lgkmcnt(0)
	s_barrier
	ds_read2st64_b32 v[24:25], v3 offset1:1
	v_cmp_eq_u32_e64 s[6:7], 0, v36
	s_and_saveexec_b64 s[8:9], s[4:5]
	s_xor_b64 s[12:13], exec, s[8:9]
	v_cmp_lt_u32_e64 s[8:9], 1, v36
	s_and_b64 s[0:1], s[8:9], exec
	s_or_saveexec_b64 s[8:9], s[12:13]
	s_waitcnt lgkmcnt(0)
	v_add_f32_e32 v5, 0, v24
	s_or_b64 s[12:13], vcc, s[6:7]
	v_cndmask_b32_e64 v7, v5, 0, s[12:13]
	v_mov_b32_e32 v5, v7
	s_xor_b64 exec, exec, s[8:9]
	s_andn2_b64 s[0:1], s[0:1], exec
	s_and_b64 s[6:7], s[6:7], exec
	v_mov_b32_e32 v5, 0
	s_or_b64 s[0:1], s[0:1], s[6:7]
	s_or_b64 exec, exec, s[8:9]
	s_and_saveexec_b64 s[6:7], s[0:1]
	v_add_f32_e32 v5, v25, v7
	s_or_b64 exec, exec, s[6:7]
	ds_read_b32 v7, v3 offset:512
	s_mov_b64 s[0:1], 0
	v_cmp_eq_u32_e64 s[6:7], 3, v36
	s_and_saveexec_b64 s[8:9], s[4:5]
	s_xor_b64 s[4:5], exec, s[8:9]
	s_cbranch_execnz .LBB0_784
	s_andn2_saveexec_b64 s[6:7], s[4:5]
	s_cbranch_execnz .LBB0_785

; #define LAS __attribute__((address_space(3)))
; template <int PASS>
; __device__ __forceinline__ void ssd_unit(LAS unsigned char* lds, int ch, int g, const bf16* PROJ, const bf16* XBC, const float* At, const float* DTt, bf16* STS, float* DECS, bf16* OMIX,
;                                          const float* d_skip, const float* ssd_norm) {
;     ...
;         SC[wave * 64 + lane] = v; DL[wave * 64 + lane] = dt;
;         if (lane == (d ? 0 : 63)) TOT[wave] = v;
;     ...
;             for (int i2 = 0; i2 < 2; ++i2) { const int idx = tid + NT * i2, tok = idx >> 4, c8 = (idx & 15) * 8;
;                 const v4u u = *(const v4u*)(XBC + (m0 + tok) * 768 + 512 + ((c8 < 64) ? 64 * g + c8 : 128 + 64 * g + (c8 - 64)));
;                 *(LAS v4u*)(((c8 < 64) ? BM : CM) + tok * RS + (c8 & 63) * 2) = u; }
;             const int p = tid & 63, hl = (tid >> 6) & 3, half = tid >> 8; const bf16* xp = XBC + (m0 + 32 * half) * 768 + (4 * g + hl) * 64 + p; unsigned xv[32];
; #pragma unroll
;             for (int jj = 0; jj < 32; ++jj) xv[jj] = xp[(size_t)jj * 768];
; #pragma unroll
;             for (int jj = 0; jj < 32; ++jj) asm volatile("" : "+v"(xv[jj]));
;             LAS unsigned char* dst = XT + (hl * 64 + p) * RS + half * 64;
; #pragma unroll
;             for (int o8 = 0; o8 < 4; ++o8) *(LAS v4u*)(dst + o8 * 16) = (v4u){xv[8 * o8] | (xv[8 * o8 + 1] << 16), xv[8 * o8 + 2] | (xv[8 * o8 + 3] << 16), xv[8 * o8 + 4] | (xv[8 * o8 + 5] << 16), xv[8 * o8 + 6] | (xv[8 * o8 + 7] << 16)};
.LBB0_825:
	s_or_b64 exec, exec, s[4:5]
	v_lshlrev_b32_e32 v123, 2, v119
	s_waitcnt lgkmcnt(0)
	v_lshl_or_b32 v4, s64, 8, v123
	s_and_b64 s[0:1], s[36:37], exec
	v_add_u32_e32 v4, 0, v4
	s_cselect_b32 s0, 63, 0
	v_add_u32_e32 v5, 0x18c00, v4
	v_add_u32_e32 v4, 0x19400, v4
	v_cmp_eq_u32_e32 vcc, s0, v119
	ds_write_b32 v5, v2
	s_waitcnt vmcnt(0)
	ds_write_b32 v4, v3
	s_and_saveexec_b64 s[0:1], vcc
	s_lshl_b32 s3, s64, 2
	s_add_i32 s3, s3, 0
	s_add_i32 s3, s3, 0x19c00
	v_mov_b32_e32 v3, s3
	ds_write_b32 v3, v2
	s_or_b64 exec, exec, s[0:1]
	v_ashrrev_i32_e32 v10, 4, v82
	v_ashrrev_i32_e32 v11, 31, v10
	v_lshlrev_b32_e32 v6, 3, v82
	v_lshl_add_u64 v[2:3], s[6:7], 0, v[10:11]
	v_mad_u64_u32 v[4:5], s[0:1], v2, s42, v[112:113]
	v_and_b32_e32 v2, 64, v6
	v_and_b32_e32 v22, 0x78, v6
	v_add_u32_e32 v2, s34, v2
	v_mad_i32_i24 v5, v3, s42, v5
	v_add_lshl_u32 v110, v2, v22, 1
	v_lshl_add_u64 v[2:3], v[4:5], 0, v[110:111]
	v_add_u32_e32 v4, 0x200, v82
	v_ashrrev_i32_e32 v12, 4, v4
	v_ashrrev_i32_e32 v84, 8, v82
	v_ashrrev_i32_e32 v13, 31, v12
	v_lshlrev_b32_e32 v14, 5, v84
	v_lshl_add_u64 v[4:5], s[6:7], 0, v[12:13]
	v_ashrrev_i32_e32 v15, 31, v14
	v_mad_u64_u32 v[6:7], s[0:1], v4, s42, v[112:113]
	v_bfe_u32 v83, v82, 6, 2
	v_lshl_add_u64 v[14:15], s[6:7], 0, v[14:15]
	v_mad_i32_i24 v7, v5, s42, v7
	v_mad_u64_u32 v[16:17], s[0:1], v14, s42, v[112:113]
	v_or_b32_e32 v11, s31, v83
	v_lshl_add_u64 v[6:7], v[6:7], 0, v[110:111]
	v_mad_i32_i24 v17, v15, s42, v17
	v_lshlrev_b32_e32 v110, 7, v11
	v_lshl_add_u64 v[14:15], v[16:17], 0, v[110:111]
	v_lshlrev_b32_e32 v110, 1, v119
	v_lshlrev_b32_e32 v164, 1, v119
	v_lshl_add_u64 v[14:15], v[14:15], 0, v[110:111]
	s_nop 0
	v_readfirstlane_b32 s98, v14
	v_readfirstlane_b32 s99, v15
	s_nop 4
	global_load_dwordx4 v[2:5], v[2:3], off offset:1024
	global_load_dwordx4 v[6:9], v[6:7], off offset:1024
	v_lshlrev_b32_e32 v11, 4, v82
	global_load_ushort v85, v164, s[98:99]
	global_load_ushort v86, v164, s[98:99] offset:1536
	global_load_ushort v87, v164, s[98:99] offset:3072
	s_add_u32 s100, s98, s44
	s_addc_u32 s101, s99, 0
	global_load_ushort v88, v164, s[100:101] offset:512
	global_load_ushort v89, v164, s[100:101] offset:2048
	global_load_ushort v90, v164, s[100:101] offset:3584
	s_add_u32 s66, s98, s45
	s_addc_u32 s67, s99, 0
	global_load_ushort v91, v164, s[66:67] offset:1024
	global_load_ushort v92, v164, s[66:67] offset:2560
	v_and_b32_e32 v11, 0x70, v11
	v_mul_lo_u32 v10, v10, s43
	s_ashr_i32 s13, s64, 1
	s_add_u32 s70, s98, s46
	s_addc_u32 s71, s99, 0
	global_load_ushort v93, v164, s[70:71]
	global_load_ushort v94, v164, s[70:71] offset:1536
	global_load_ushort v95, v164, s[70:71] offset:3072
	s_add_u32 s100, s98, s47
	s_addc_u32 s101, s99, 0
	global_load_ushort v96, v164, s[100:101] offset:512
	global_load_ushort v97, v164, s[100:101] offset:2048
	global_load_ushort v98, v164, s[100:101] offset:3584
	s_add_u32 s66, s98, s50
	s_addc_u32 s67, s99, 0
	global_load_ushort v99, v164, s[66:67] offset:1024
	global_load_ushort v100, v164, s[66:67] offset:2560
	s_add_i32 s0, s13, s31
	s_lshl_b32 s1, s8, 4
	s_lshl_b32 s3, s0, 1
	s_add_u32 s70, s98, s51
	s_addc_u32 s71, s99, 0
	global_load_ushort v101, v164, s[70:71]
	global_load_ushort v102, v164, s[70:71] offset:1536
	global_load_ushort v103, v164, s[70:71] offset:3072
	s_add_u32 s100, s98, s52
	s_addc_u32 s101, s99, 0
	global_load_ushort v104, v164, s[100:101] offset:512
	global_load_ushort v105, v164, s[100:101] offset:2048
	global_load_ushort v106, v164, s[100:101] offset:3584
	s_add_u32 s66, s98, s53
	s_addc_u32 s67, s99, 0
	global_load_ushort v107, v164, s[66:67] offset:1024
	global_load_ushort v108, v164, s[66:67] offset:2560
	s_add_i32 s4, s3, s1
	s_ashr_i32 s5, s4, 31
	s_add_u32 s72, s98, s56
	s_addc_u32 s73, s99, 0
	v_and_b32_e32 v140, 15, v82
	s_add_u32 s70, s98, s54
	s_addc_u32 s71, s99, 0
	global_load_ushort v109, v164, s[70:71]
	global_load_ushort v121, v164, s[70:71] offset:1536
	global_load_ushort v144, v164, s[70:71] offset:3072
	s_add_u32 s100, s98, s55
	s_addc_u32 s101, s99, 0
	global_load_ushort v145, v164, s[100:101] offset:512
	global_load_ushort v146, v164, s[100:101] offset:2048
	global_load_ushort v147, v164, s[100:101] offset:3584
	global_load_ushort v148, v164, s[72:73] offset:1024
	global_load_ushort v149, v164, s[72:73] offset:2560
	v_cmp_gt_u32_e32 vcc, 64, v22
	s_lshl_b64 s[8:9], s[4:5], 13
	s_or_b32 s4, s4, 1
	v_cndmask_b32_e32 v13, 0, v1, vcc
	v_add3_u32 v10, v13, v10, v11
	s_ashr_i32 s5, s4, 31
	s_lshl_b64 s[4:5], s[4:5], 13
	s_and_b32 s12, s64, 1
	s_lshl_b32 s3, s12, 5
	v_or_b32_e32 v143, s3, v140
	v_or_b32_e32 v120, s6, v143
	v_lshrrev_b32_e32 v142, 4, v119
	v_lshlrev_b32_e32 v110, 3, v142
	v_or_b32_e32 v141, 16, v143
	v_or_b32_e32 v118, s6, v141
	s_ashr_i32 s1, s0, 31
	v_lshl_or_b32 v83, v83, 6, v119
	v_mul_u32_u24_e32 v83, 0x90, v83
	v_lshlrev_b32_e32 v84, 6, v84
	v_add3_u32 v83, 0, v83, v84
	v_mov_b32_e32 v150, 0
	v_mov_b32_e32 v153, 0
	s_waitcnt vmcnt(33)
	ds_write_b128 v10, v[2:5]
	v_mul_lo_u32 v2, v12, s43
	v_add3_u32 v2, v13, v2, v11
	s_waitcnt vmcnt(32)
	ds_write_b128 v2, v[6:9]
	v_and_b32_e32 v2, 48, v119
	v_mov_b32_e32 v3, v111
	v_lshl_add_u64 v[4:5], s[28:29], 0, v[2:3]
	v_lshl_add_u64 v[6:7], v[4:5], 0, s[8:9]
	v_lshlrev_b32_e32 v8, 7, v140
	v_mov_b32_e32 v9, v111
	v_lshl_add_u64 v[10:11], v[6:7], 0, v[8:9]
	s_waitcnt vmcnt(31)
; #define LAS __attribute__((address_space(3)))
; #define MFMA16(a, b, c) __builtin_amdgcn_mfma_f32_16x16x32_bf16((a), (b), (c), 0, 0, 0)
; template <int PASS>
; __device__ __forceinline__ void ssd_unit(LAS unsigned char* lds, int ch, int g, const bf16* PROJ, const bf16* XBC, const float* At, const float* DTt, bf16* STS, float* DECS, bf16* OMIX,
;                                          const float* d_skip, const float* ssd_norm) {
;     ...
;             for (int jj = 0; jj < 32; ++jj) asm volatile("" : "+v"(xv[jj]));
;             LAS unsigned char* dst = XT + (hl * 64 + p) * RS + half * 64;
; #pragma unroll
;             for (int o8 = 0; o8 < 4; ++o8) *(LAS v4u*)(dst + o8 * 16) = (v4u){xv[8 * o8] | (xv[8 * o8 + 1] << 16), xv[8 * o8 + 2] | (xv[8 * o8 + 3] << 16), xv[8 * o8 + 4] | (xv[8 * o8 + 5] << 16), xv[8 * o8 + 6] | (xv[8 * o8 + 7] << 16)};
;         }
;         const int hl = wave >> 1, ih = wave & 1, hh = 4 * g + hl;
;         bf16x8 sf[2][4][2];
; #pragma unroll
;         for (int d = 0; d < 2; ++d)
; #pragma unroll
;             for (int pt = 0; pt < 4; ++pt)
; #pragma unroll
;                 for (int ks = 0; ks < 2; ++ks) sf[d][pt][ks] = *(const bf16x8*)(STS + (size_t)((ch * 8 + hh) * 2 + d) * 4096 + (16 * pt + lr) * 64 + 32 * ks + 8 * lq);
;         v2u zz8[2][4];
; #pragma unroll
;         for (int i2 = 0; i2 < 2; ++i2)
; #pragma unroll
;             for (int pt = 0; pt < 4; ++pt) zz8[i2][pt] = *(const v2u*)(PROJ + (m0 + 16 * (2 * ih + i2) + lr) * LDP + PZ + hh * 64 + 16 * pt + 4 * lq);
;         const float ds_e = d_skip[hh];
;         f32x4 gn8[4];
; #pragma unroll
;         for (int pt = 0; pt < 4; ++pt) gn8[pt] = *(const f32x4*)(ssd_norm + 256 * g + 64 * hl + 16 * pt + 4 * lq);
;         __syncthreads();
;         {
;             const int ait = wave >> 1, i = 16 * ait + lr;
; #pragma unroll
;             for (int j2 = 0; j2 < 2; ++j2) { const int jt = 2 * (wave & 1) + j2, j0 = 16 * jt + 4 * lq; pg8::f32x4 cb = {0.f, 0.f, 0.f, 0.f};
;                 cb = MFMA16(ldsfrag(BM, 16 * jt + lr, 0, lq), ldsfrag(CM, 16 * ait + lr, 0, lq), cb); cb = MFMA16(ldsfrag(BM, 16 * jt + lr, 1, lq), ldsfrag(CM, 16 * ait + lr, 1, lq), cb);
; #pragma unroll
;                 for (int h4 = 0; h4 < 4; ++h4) { const float sfi = SC[h4 * 64 + i], sbi = SC[(4 + h4) * 64 + i]; float p[4];
	s_waitcnt vmcnt(30)
	s_waitcnt vmcnt(29)
	s_waitcnt vmcnt(28)
	s_waitcnt vmcnt(27)
	s_waitcnt vmcnt(26)
	s_waitcnt vmcnt(25)
	s_waitcnt vmcnt(24)
	s_waitcnt vmcnt(23)
	s_waitcnt vmcnt(22)
	s_waitcnt vmcnt(21)
	s_waitcnt vmcnt(20)
	s_waitcnt vmcnt(19)
	s_waitcnt vmcnt(18)
	s_waitcnt vmcnt(17)
	s_waitcnt vmcnt(16)
	s_waitcnt vmcnt(15)
	s_waitcnt vmcnt(14)
	s_waitcnt vmcnt(13)
	s_waitcnt vmcnt(12)
	s_waitcnt vmcnt(11)
	s_waitcnt vmcnt(10)
	s_waitcnt vmcnt(9)
	s_waitcnt vmcnt(8)
	s_waitcnt vmcnt(7)
	s_waitcnt vmcnt(6)
	s_waitcnt vmcnt(5)
	s_waitcnt vmcnt(4)
	s_waitcnt vmcnt(3)
	s_waitcnt vmcnt(2)
	s_waitcnt vmcnt(1)
	s_waitcnt vmcnt(0)
	global_load_dwordx4 v[70:73], v[10:11], off
	global_load_dwordx4 v[46:49], v[10:11], off offset:64
	global_load_dwordx4 v[62:65], v[10:11], off offset:2048
	global_load_dwordx4 v[30:33], v[10:11], off offset:2112
	v_or_b32_e32 v10, 0x1000, v8
	v_mov_b32_e32 v11, v111
	v_lshl_add_u64 v[12:13], v[6:7], 0, v[10:11]
	global_load_dwordx4 v[54:57], v[12:13], off
	global_load_dwordx4 v[22:25], v[12:13], off offset:64
	v_or_b32_e32 v12, 0x1800, v8
	v_mov_b32_e32 v13, v111
	v_lshl_add_u64 v[6:7], v[6:7], 0, v[12:13]
	v_lshl_add_u64 v[4:5], v[4:5], 0, s[4:5]
	global_load_dwordx4 v[50:53], v[6:7], off
	global_load_dwordx4 v[18:21], v[6:7], off offset:64
	v_lshl_add_u64 v[6:7], v[4:5], 0, v[8:9]
	global_load_dwordx4 v[78:81], v[6:7], off
	global_load_dwordx4 v[42:45], v[6:7], off offset:64
	global_load_dwordx4 v[74:77], v[6:7], off offset:2048
	global_load_dwordx4 v[38:41], v[6:7], off offset:2112
	v_lshl_add_u64 v[6:7], v[4:5], 0, v[10:11]
	v_lshl_add_u64 v[4:5], v[4:5], 0, v[12:13]
	s_lshl_b32 s4, s0, 6
	global_load_dwordx4 v[66:69], v[6:7], off
	global_load_dwordx4 v[34:37], v[6:7], off offset:64
	global_load_dwordx4 v[58:61], v[4:5], off
	global_load_dwordx4 v[26:29], v[4:5], off offset:64
	s_ashr_i32 s5, s4, 31
	v_mad_u64_u32 v[4:5], s[8:9], v120, s57, v[114:115]
	v_mad_i32_i24 v5, s7, v117, v5
	s_lshl_b64 s[4:5], s[4:5], 1
	v_lshl_add_u64 v[4:5], v[4:5], 0, s[4:5]
	v_lshl_add_u64 v[4:5], v[4:5], 0, v[110:111]
	global_load_dwordx2 v[138:139], v[4:5], off offset:3072
	global_load_dwordx2 v[136:137], v[4:5], off offset:3104
	global_load_dwordx2 v[134:135], v[4:5], off offset:3136
	global_load_dwordx2 v[132:133], v[4:5], off offset:3168
	v_mad_u64_u32 v[4:5], s[8:9], v118, s57, v[114:115]
	s_lshl_b64 s[0:1], s[0:1], 2
	v_mad_i32_i24 v5, s7, v117, v5
	s_add_u32 s0, s48, s0
	v_lshl_add_u64 v[4:5], v[4:5], 0, s[4:5]
	s_addc_u32 s1, s49, s1
	s_lshl_b32 s36, s13, 6
	v_lshl_add_u64 v[4:5], v[4:5], 0, v[110:111]
	s_ashr_i32 s37, s36, 31
	global_load_dwordx2 v[130:131], v[4:5], off offset:3072
	global_load_dwordx2 v[128:129], v[4:5], off offset:3104
	global_load_dwordx2 v[126:127], v[4:5], off offset:3136
	global_load_dwordx2 v[124:125], v[4:5], off offset:3168
	global_load_dword v122, v111, s[0:1]
	s_lshl_b64 s[0:1], s[36:37], 2
	s_add_u32 s0, s40, s0
	s_addc_u32 s1, s41, s1
	global_load_dwordx4 v[14:17], v2, s[0:1]
	global_load_dwordx4 v[10:13], v2, s[0:1] offset:64
	global_load_dwordx4 v[6:9], v2, s[0:1] offset:128
	s_nop 0
	global_load_dwordx4 v[2:5], v2, s[0:1] offset:192
	v_lshl_or_b32 v84, v86, 16, v85
	v_lshl_or_b32 v85, v88, 16, v87
	v_lshl_or_b32 v86, v90, 16, v89
	v_lshl_or_b32 v87, v92, 16, v91
	ds_write_b128 v83, v[84:87] offset:27648
	v_lshl_or_b32 v84, v94, 16, v93
	v_lshl_or_b32 v85, v96, 16, v95
	v_lshl_or_b32 v86, v98, 16, v97
	v_lshl_or_b32 v87, v100, 16, v99
	ds_write_b128 v83, v[84:87] offset:27664
	v_lshl_or_b32 v84, v102, 16, v101
	v_lshl_or_b32 v85, v104, 16, v103
	v_lshl_or_b32 v86, v106, 16, v105
	v_lshl_or_b32 v87, v108, 16, v107
	ds_write_b128 v83, v[84:87] offset:27680
	v_lshl_or_b32 v84, v121, 16, v109
	v_lshl_or_b32 v85, v145, 16, v144
	v_lshl_or_b32 v86, v147, 16, v146
	v_lshl_or_b32 v87, v149, 16, v148
	v_and_b32_e32 v144, 48, v82
	v_mul_u32_u24_e32 v145, 0x90, v143
	ds_write_b128 v83, v[84:87] offset:27696
	v_add3_u32 v86, 0, v145, v144
	s_waitcnt lgkmcnt(0)
	s_barrier
	ds_read_b128 v[90:93], v86 offset:9216
	v_lshl_or_b32 v146, s13, 4, v140
	v_mul_lo_u32 v148, v146, s43
	v_add3_u32 v87, 0, v148, v144
	ds_read_b128 v[82:85], v87
	ds_read_b128 v[94:97], v86 offset:9280
	ds_read_b128 v[86:89], v87 offset:64
	s_waitcnt lgkmcnt(2)
	v_mfma_f32_16x16x32_bf16 v[90:93], v[90:93], v[82:85], 0
	v_lshlrev_b32_e32 v110, 2, v142
	v_or_b32_e32 v155, s3, v110
	s_add_i32 s3, 0, 0x18c00
	s_waitcnt lgkmcnt(0)
	v_mfma_f32_16x16x32_bf16 v[90:93], v[94:97], v[86:89], v[90:93]
	v_lshlrev_b32_e32 v94, 2, v155
	v_add_u32_e32 v95, 0, v94
	v_add_u32_e32 v158, s3, v94
	v_add_u32_e32 v156, 0x19400, v95
	v_lshlrev_b32_e32 v95, 2, v146
	v_add_u32_e32 v94, s58, v94
	v_add_u32_e32 v147, s3, v95
	v_add_u32_e32 v149, s58, v95
	ds_read_b128 v[94:97], v94
	ds_read_b128 v[106:109], v158
	ds_read_b128 v[102:105], v156
	ds_read_b32 v151, v147
	ds_read_b32 v152, v149
	ds_read_b128 v[98:101], v156 offset:1024
	s_lshl_b32 s26, s12, 1
	s_cmp_le_i32 s26, s13
	v_mov_b32_e32 v121, s7
	s_cselect_b64 s[0:1], -1, 0
	s_cmp_gt_i32 s26, s13
	v_cmp_le_i32_e32 vcc, v155, v146
	s_cbranch_scc1 .LBB0_829
	s_waitcnt lgkmcnt(2)
	v_sub_f32_e32 v106, v151, v106
	v_min_f32_e32 v106, 0, v106
	v_mul_f32_e32 v106, 0x3fb8aa3b, v106
	v_exp_f32_e32 v106, v106
	s_nop 0
	v_mul_f32_e32 v102, v102, v106
	v_cndmask_b32_e32 v153, 0, v102, vcc
